# gemm1+gemm2 main loops: hand-written 3-stage LDS-DMA ring with counted vmcnt; gemm2 epilogue x loads hoisted above main loop (de-serialized)
# speedup vs baseline: 1.0268x; 1.0268x over previous
.LBB0_213:
	s_andn2_b64 vcc, exec, s[6:7]
	s_mov_b64 s[6:7], 0
	s_cbranch_vccnz .LBB0_209
	s_ashr_i32 s39, s38, 31
	s_lshl_b64 s[6:7], s[38:39], 18
	s_add_u32 s72, s3, s6
	s_addc_u32 s73, s33, s7
	s_ashr_i32 s11, s10, 31
	s_lshl_b64 s[34:35], s[10:11], 19
	s_add_u32 s74, s50, s34
	s_addc_u32 s75, s51, s35
	v_readfirstlane_b32 s11, v184
	s_nop 3
	s_lshr_b32 s0, s11, 6
	s_lshr_b32 s39, s11, 4
	s_and_b32 s39, s39, 4
	v_lshl_or_b32 v2, s0, 3, v210
	v_bitop3_b32 v8, s39, v208, v209 bitop3:0x36
	v_lshlrev_b32_e32 v2, 11, v2
	v_lshlrev_b32_e32 v8, 4, v8
	v_or_b32_e32 v144, v2, v8
	v_add_u32_e32 v145, 0x20000, v144
	v_add_u32_e32 v146, 0x40000, v144
	v_add_u32_e32 v147, 0x60000, v144
	s_lshl_b32 s79, s0, 10
	s_lshr_b32 s9, s11, 1
	s_and_b32 s9, s9, 0x1ffffc0
	v_and_or_b32 v4, s11, 64, v189
	v_lshlrev_b32_e32 v106, 7, v4
	v_or_b32_e32 v4, s9, v189
	v_lshlrev_b32_e32 v107, 7, v4
	s_movk_i32 s76, 0x100
	s_mov_b32 s77, 0xc100
	s_mov_b32 s78, 0x1b900
	s_add_i32 s81, s76, s79
	s_mov_b32 m0, s81
	s_nop 0
	global_load_lds_dwordx4 v144, s[72:73]
	s_add_i32 m0, s81, 0x2000
	s_nop 0
	global_load_lds_dwordx4 v145, s[72:73]
	s_add_i32 m0, s81, 0x4000
	s_nop 0
	global_load_lds_dwordx4 v144, s[74:75]
	s_add_i32 m0, s81, 0x6000
	s_nop 0
	global_load_lds_dwordx4 v145, s[74:75]
	s_add_i32 m0, s81, 0x8000
	s_nop 0
	global_load_lds_dwordx4 v146, s[74:75]
	s_add_i32 m0, s81, 0xa000
	s_nop 0
	global_load_lds_dwordx4 v147, s[74:75]
	s_add_u32 s72, s72, 0x80
	s_addc_u32 s73, s73, 0
	s_add_u32 s74, s74, 0x80
	s_addc_u32 s75, s75, 0
	s_add_i32 s81, s77, s79
	s_mov_b32 m0, s81
	s_nop 0
	global_load_lds_dwordx4 v144, s[72:73]
	s_add_i32 m0, s81, 0x2000
	s_nop 0
	global_load_lds_dwordx4 v145, s[72:73]
	s_add_i32 m0, s81, 0x4000
	s_nop 0
	global_load_lds_dwordx4 v144, s[74:75]
	s_add_i32 m0, s81, 0x6000
	s_nop 0
	global_load_lds_dwordx4 v145, s[74:75]
	s_add_i32 m0, s81, 0x8000
	s_nop 0
	global_load_lds_dwordx4 v146, s[74:75]
	s_add_i32 m0, s81, 0xa000
	s_nop 0
	global_load_lds_dwordx4 v147, s[74:75]
	s_add_u32 s72, s72, 0x80
	s_addc_u32 s73, s73, 0
	s_add_u32 s74, s74, 0x80
	s_addc_u32 s75, s75, 0
	v_mov_b32_e32 v50, 0
	v_mov_b32_e32 v51, 0
	v_mov_b32_e32 v52, 0
	v_mov_b32_e32 v53, 0
	v_mov_b32_e32 v54, 0
	v_mov_b32_e32 v55, 0
	v_mov_b32_e32 v56, 0
	v_mov_b32_e32 v57, 0
	v_mov_b32_e32 v58, 0
	v_mov_b32_e32 v59, 0
	v_mov_b32_e32 v60, 0
	v_mov_b32_e32 v61, 0
	v_mov_b32_e32 v62, 0
	v_mov_b32_e32 v63, 0
	v_mov_b32_e32 v64, 0
	v_mov_b32_e32 v65, 0
	v_mov_b32_e32 v18, 0
	v_mov_b32_e32 v19, 0
	v_mov_b32_e32 v20, 0
	v_mov_b32_e32 v21, 0
	v_mov_b32_e32 v22, 0
	v_mov_b32_e32 v23, 0
	v_mov_b32_e32 v24, 0
	v_mov_b32_e32 v25, 0
	v_mov_b32_e32 v26, 0
	v_mov_b32_e32 v27, 0
	v_mov_b32_e32 v28, 0
	v_mov_b32_e32 v29, 0
	v_mov_b32_e32 v30, 0
	v_mov_b32_e32 v31, 0
	v_mov_b32_e32 v32, 0
	v_mov_b32_e32 v33, 0
	v_mov_b32_e32 v34, 0
	v_mov_b32_e32 v35, 0
	v_mov_b32_e32 v36, 0
	v_mov_b32_e32 v37, 0
	v_mov_b32_e32 v38, 0
	v_mov_b32_e32 v39, 0
	v_mov_b32_e32 v40, 0
	v_mov_b32_e32 v41, 0
	v_mov_b32_e32 v42, 0
	v_mov_b32_e32 v43, 0
	v_mov_b32_e32 v44, 0
	v_mov_b32_e32 v45, 0
	v_mov_b32_e32 v46, 0
	v_mov_b32_e32 v47, 0
	v_mov_b32_e32 v48, 0
	v_mov_b32_e32 v49, 0
	v_mov_b32_e32 v2, 0
	v_mov_b32_e32 v3, 0
	v_mov_b32_e32 v4, 0
	v_mov_b32_e32 v5, 0
	v_mov_b32_e32 v6, 0
	v_mov_b32_e32 v7, 0
	v_mov_b32_e32 v8, 0
	v_mov_b32_e32 v9, 0
	v_mov_b32_e32 v10, 0
	v_mov_b32_e32 v11, 0
	v_mov_b32_e32 v12, 0
	v_mov_b32_e32 v13, 0
	v_mov_b32_e32 v14, 0
	v_mov_b32_e32 v15, 0
	v_mov_b32_e32 v16, 0
	v_mov_b32_e32 v17, 0
	v_add_u32_e32 v124, s76, v106
	v_add_u32_e32 v125, s76, v107
	s_mov_b32 s80, 0
	s_waitcnt vmcnt(6)
	s_barrier
	v_add_u32_e32 v142, v124, v211
	v_add_u32_e32 v143, v125, v211
	ds_read_b128 v[108:111], v142
	ds_read_b128 v[116:119], v143 offset:16384
	ds_read_b128 v[120:123], v143 offset:20480
	ds_read_b128 v[112:115], v142 offset:4096
.Lg1_loop:
	s_cmp_ge_u32 s80, 14
	s_cbranch_scc1 .Lg1_nodma
	s_add_i32 s81, s78, s79
	s_mov_b32 m0, s81
	s_nop 0
	global_load_lds_dwordx4 v144, s[72:73]
	s_add_i32 m0, s81, 0x2000
	s_nop 0
	global_load_lds_dwordx4 v145, s[72:73]
	s_add_i32 m0, s81, 0x4000
	s_nop 0
	global_load_lds_dwordx4 v144, s[74:75]
	s_add_i32 m0, s81, 0x6000
	s_nop 0
	global_load_lds_dwordx4 v145, s[74:75]
	s_add_i32 m0, s81, 0x8000
	s_nop 0
	global_load_lds_dwordx4 v146, s[74:75]
	s_add_i32 m0, s81, 0xa000
	s_nop 0
	global_load_lds_dwordx4 v147, s[74:75]
	s_add_u32 s72, s72, 0x80
	s_addc_u32 s73, s73, 0
	s_add_u32 s74, s74, 0x80
	s_addc_u32 s75, s75, 0
.Lg1_nodma:
	v_add_u32_e32 v142, v124, v212
	v_add_u32_e32 v143, v125, v212
	ds_read_b128 v[126:129], v142
	ds_read_b128 v[134:137], v143 offset:16384
	ds_read_b128 v[138:141], v143 offset:20480
	ds_read_b128 v[130:133], v142 offset:4096
	s_setprio 1
	s_waitcnt lgkmcnt(6)
	v_mfma_f32_32x32x16_bf16 v[50:65], v[108:111], v[116:119], v[50:65]
	s_waitcnt lgkmcnt(5)
	v_mfma_f32_32x32x16_bf16 v[18:33], v[108:111], v[120:123], v[18:33]
	s_waitcnt lgkmcnt(4)
	v_mfma_f32_32x32x16_bf16 v[34:49], v[112:115], v[116:119], v[34:49]
	v_mfma_f32_32x32x16_bf16 v[2:17], v[112:115], v[120:123], v[2:17]
	s_setprio 0
	v_add_u32_e32 v142, v124, v213
	v_add_u32_e32 v143, v125, v213
	ds_read_b128 v[108:111], v142
	ds_read_b128 v[116:119], v143 offset:16384
	ds_read_b128 v[120:123], v143 offset:20480
	ds_read_b128 v[112:115], v142 offset:4096
	s_setprio 1
	s_waitcnt lgkmcnt(6)
	v_mfma_f32_32x32x16_bf16 v[50:65], v[126:129], v[134:137], v[50:65]
	s_waitcnt lgkmcnt(5)
	v_mfma_f32_32x32x16_bf16 v[18:33], v[126:129], v[138:141], v[18:33]
	s_waitcnt lgkmcnt(4)
	v_mfma_f32_32x32x16_bf16 v[34:49], v[130:133], v[134:137], v[34:49]
	v_mfma_f32_32x32x16_bf16 v[2:17], v[130:133], v[138:141], v[2:17]
	s_setprio 0
	v_add_u32_e32 v142, v124, v214
	v_add_u32_e32 v143, v125, v214
	ds_read_b128 v[126:129], v142
	ds_read_b128 v[134:137], v143 offset:16384
	ds_read_b128 v[138:141], v143 offset:20480
	ds_read_b128 v[130:133], v142 offset:4096
	s_setprio 1
	s_waitcnt lgkmcnt(6)
	v_mfma_f32_32x32x16_bf16 v[50:65], v[108:111], v[116:119], v[50:65]
	s_waitcnt lgkmcnt(5)
	v_mfma_f32_32x32x16_bf16 v[18:33], v[108:111], v[120:123], v[18:33]
	s_waitcnt lgkmcnt(4)
	v_mfma_f32_32x32x16_bf16 v[34:49], v[112:115], v[116:119], v[34:49]
	v_mfma_f32_32x32x16_bf16 v[2:17], v[112:115], v[120:123], v[2:17]
	s_setprio 0
	s_waitcnt lgkmcnt(0)
	s_cmp_ge_u32 s80, 14
	s_cbranch_scc1 .Lg1_w0
	s_waitcnt vmcnt(6)
	s_branch .Lg1_wd

.Lg1_wd:
	s_barrier
	s_add_i32 s80, s80, 1
	s_mov_b32 s81, s76
	s_mov_b32 s76, s77
	s_mov_b32 s77, s78
	s_mov_b32 s78, s81
	s_cmp_eq_u32 s80, 16
	s_cbranch_scc1 .Lg1_done
	v_add_u32_e32 v124, s76, v106
	v_add_u32_e32 v125, s76, v107
	v_add_u32_e32 v142, v124, v211
	v_add_u32_e32 v143, v125, v211
	ds_read_b128 v[108:111], v142
	ds_read_b128 v[116:119], v143 offset:16384
	ds_read_b128 v[120:123], v143 offset:20480
	ds_read_b128 v[112:115], v142 offset:4096
	s_setprio 1
	v_mfma_f32_32x32x16_bf16 v[50:65], v[126:129], v[134:137], v[50:65]
	v_mfma_f32_32x32x16_bf16 v[18:33], v[126:129], v[138:141], v[18:33]
	v_mfma_f32_32x32x16_bf16 v[34:49], v[130:133], v[134:137], v[34:49]
	v_mfma_f32_32x32x16_bf16 v[2:17], v[130:133], v[138:141], v[2:17]
	s_setprio 0
	s_branch .Lg1_loop
.Lg1_done:
	s_setprio 1
	v_mfma_f32_32x32x16_bf16 v[50:65], v[126:129], v[134:137], v[50:65]
	v_mfma_f32_32x32x16_bf16 v[18:33], v[126:129], v[138:141], v[18:33]
	v_mfma_f32_32x32x16_bf16 v[34:49], v[130:133], v[134:137], v[34:49]
	v_mfma_f32_32x32x16_bf16 v[2:17], v[130:133], v[138:141], v[2:17]
	s_setprio 0
	s_ashr_i32 s11, s38, 2
	s_waitcnt vmcnt(0)
	s_cmp_lt_u32 s38, 4
	s_cselect_b64 s[40:41], -1, 0
	s_mov_b64 s[8:9], -1
	s_and_b64 vcc, exec, s[40:41]
	s_mov_b64 s[36:37], -1
	s_cbranch_vccnz .LBB0_219
	s_cmp_gt_u32 s11, 5
	s_mov_b64 s[36:37], 0
	s_cbranch_scc1 .LBB0_219
	s_lshr_b32 s0, s38, 2
	s_lshr_b32 s0, 50, s0
	s_bitcmp1_b32 s0, 0
	s_cselect_b64 s[36:37], -1, 0

.LBB0_868:
	s_ashr_i32 s24, s47, 2
	s_and_b32 s48, s47, 3
	s_lshl_b32 s48, s48, 8
	s_ashr_i32 s25, s24, 31
	s_lshl_b64 s[26:27], s[24:25], 18
	s_add_u32 s12, s38, s26
	s_addc_u32 s13, s39, s27
	s_lshl_b32 s25, s48, 11
	s_add_u32 s14, s40, s25
	s_addc_u32 s15, s41, 0
	v_readfirstlane_b32 s34, v184
	s_nop 3
	s_lshr_b32 s49, s34, 6
	s_and_b32 s25, s34, 64
	s_lshl_b32 s4, s24, 7
	s_or_b32 s30, s25, s4
	s_cmpk_gt_i32 s30, 0x3fff
	s_cbranch_scc0 .Lg2_prompt
	s_add_i32 s4, s30, 0xffffc000
	s_lshr_b32 s24, s4, 6
	s_mulk_i32 s24, 0xc00
	s_add_i32 s28, s24, 0xc00
	s_lshl_b64 s[26:27], s[4:5], 12
	s_add_u32 s24, s42, s26
	s_addc_u32 s25, s43, s27
	s_ashr_i32 s29, s28, 31
	s_mov_b64 s[34:35], s[0:1]
	s_branch .Lg2_ptr
.Lg2_prompt:
	v_readlane_b32 s34, v247, 0
	v_readlane_b32 s35, v247, 1
	s_ashr_i32 s31, s30, 31
	s_lshl_b64 s[26:27], s[30:31], 12
	s_add_u32 s24, s52, s26
	s_addc_u32 s25, s53, s27
	s_mov_b64 s[28:29], 0
	s_nop 1
.Lg2_ptr:
	s_load_dwordx2 s[30:31], s[34:35], 0x0
	v_readfirstlane_b32 s34, v184
	s_nop 3
	s_lshr_b32 s6, s34, 4
	s_and_b32 s6, s6, 4
	v_bitop3_b32 v6, s6, v208, v209 bitop3:0x36
	v_lshl_or_b32 v2, s49, 3, v210
	v_lshlrev_b32_e32 v2, 11, v2
	v_lshlrev_b32_e32 v6, 4, v6
	v_or_b32_e32 v124, v2, v6
	v_add_u32_e32 v125, 0x20000, v124
	v_add_u32_e32 v126, 0x40000, v124
	v_add_u32_e32 v127, 0x60000, v124
	s_lshl_b32 s19, s49, 10
	s_and_b32 s6, s34, 64
	v_or_b32_e32 v2, s6, v189
	v_lshlrev_b32_e32 v118, 7, v2
	s_lshr_b32 s6, s34, 1
	s_and_b32 s50, s6, 0x7fffffc0
	v_or_b32_e32 v2, s50, v189
	v_lshlrev_b32_e32 v119, 7, v2
	s_mulk_i32 s49, 0x3000
	s_add_i32 s34, s49, 0x100
	v_add3_u32 v240, s34, v72, v74
	v_add3_u32 v83, s34, v187, v73
	s_add_i32 s4, s50, s48
	v_add_u32_e32 v216, s4, v75
	v_add_u32_e32 v217, s4, v76
	v_add_u32_e32 v218, s4, v77
	v_add_u32_e32 v219, s4, v78
	v_add_u32_e32 v220, s4, v79
	v_add_u32_e32 v221, s4, v80
	v_add_u32_e32 v222, s4, v81
	v_add_u32_e32 v223, s4, v82
	v_lshlrev_b32_e32 v216, 2, v216
	v_lshlrev_b32_e32 v217, 2, v217
	v_lshlrev_b32_e32 v218, 2, v218
	v_lshlrev_b32_e32 v219, 2, v219
	v_lshlrev_b32_e32 v220, 2, v220
	v_lshlrev_b32_e32 v221, 2, v221
	v_lshlrev_b32_e32 v222, 2, v222
	v_lshlrev_b32_e32 v223, 2, v223
	v_lshlrev_b32_e32 v68, 2, v188
	s_lshl_b64 s[28:29], s[28:29], 2
	s_add_u32 s6, s54, s28
	s_addc_u32 s7, s55, s29
	s_lshl_b64 s[28:29], s[4:5], 2
	s_add_u32 s28, s6, s28
	s_addc_u32 s29, s7, s29
	v_lshl_add_u64 v[64:65], s[28:29], 0, v[68:69]
	v_add_co_u32_e32 v64, vcc, s46, v64
	s_nop 1
	v_addc_co_u32_e32 v65, vcc, 0, v65, vcc
	s_waitcnt lgkmcnt(0)
	s_add_u32 s26, s30, s26
	s_addc_u32 s27, s31, s27
	s_add_u32 s8, s26, 0x20000
	s_addc_u32 s9, s27, 0
	s_add_u32 s10, s24, 0x20000
	s_addc_u32 s11, s25, 0
	s_movk_i32 s16, 0x100
	s_mov_b32 s17, 0xc100
	s_mov_b32 s18, 0x1b900
	s_add_i32 s21, s16, s19
	s_mov_b32 m0, s21
	s_nop 0
	global_load_lds_dwordx4 v124, s[12:13]
	s_add_i32 m0, s21, 0x2000
	s_nop 0
	global_load_lds_dwordx4 v125, s[12:13]
	s_add_i32 m0, s21, 0x4000
	s_nop 0
	global_load_lds_dwordx4 v124, s[14:15]
	s_add_i32 m0, s21, 0x6000
	s_nop 0
	global_load_lds_dwordx4 v125, s[14:15]
	s_add_i32 m0, s21, 0x8000
	s_nop 0
	global_load_lds_dwordx4 v126, s[14:15]
	s_add_i32 m0, s21, 0xa000
	s_nop 0
	global_load_lds_dwordx4 v127, s[14:15]
	s_add_u32 s12, s12, 0x80
	s_addc_u32 s13, s13, 0
	s_add_u32 s14, s14, 0x80
	s_addc_u32 s15, s15, 0
	s_add_i32 s21, s17, s19
	s_mov_b32 m0, s21
	s_nop 0
	global_load_lds_dwordx4 v124, s[12:13]
	s_add_i32 m0, s21, 0x2000
	s_nop 0
	global_load_lds_dwordx4 v125, s[12:13]
	s_add_i32 m0, s21, 0x4000
	s_nop 0
	global_load_lds_dwordx4 v124, s[14:15]
	s_add_i32 m0, s21, 0x6000
	s_nop 0
	global_load_lds_dwordx4 v125, s[14:15]
	s_add_i32 m0, s21, 0x8000
	s_nop 0
	global_load_lds_dwordx4 v126, s[14:15]
	s_add_i32 m0, s21, 0xa000
	s_nop 0
	global_load_lds_dwordx4 v127, s[14:15]
	s_add_u32 s12, s12, 0x80
	s_addc_u32 s13, s13, 0
	s_add_u32 s14, s14, 0x80
	s_addc_u32 s15, s15, 0
	global_load_dwordx4 v[64:67], v[64:65], off
	global_load_dwordx4 v[128:131], v216, s[26:27]
	global_load_dwordx4 v[132:135], v217, s[26:27]
	global_load_dwordx4 v[136:139], v218, s[26:27]
	global_load_dwordx4 v[140:143], v219, s[26:27]
	global_load_dwordx4 v[144:147], v220, s[26:27]
	global_load_dwordx4 v[148:151], v221, s[26:27]
	global_load_dwordx4 v[152:155], v222, s[26:27]
	global_load_dwordx4 v[156:159], v223, s[26:27]
	global_load_dwordx4 v[160:163], v216, s[8:9]
	global_load_dwordx4 v[164:167], v217, s[8:9]
	global_load_dwordx4 v[168:171], v218, s[8:9]
	global_load_dwordx4 v[172:175], v219, s[8:9]
	global_load_dwordx4 v[176:179], v220, s[8:9]
	global_load_dwordx4 v[180:183], v221, s[8:9]
	global_load_dwordx4 v[190:193], v222, s[8:9]
	global_load_dwordx4 v[194:197], v223, s[8:9]
	v_mov_b32_e32 v48, 0
	v_mov_b32_e32 v49, 0
	v_mov_b32_e32 v50, 0
	v_mov_b32_e32 v51, 0
	v_mov_b32_e32 v52, 0
	v_mov_b32_e32 v53, 0
	v_mov_b32_e32 v54, 0
	v_mov_b32_e32 v55, 0
	v_mov_b32_e32 v56, 0
	v_mov_b32_e32 v57, 0
	v_mov_b32_e32 v58, 0
	v_mov_b32_e32 v59, 0
	v_mov_b32_e32 v60, 0
	v_mov_b32_e32 v61, 0
	v_mov_b32_e32 v62, 0
	v_mov_b32_e32 v63, 0
	v_mov_b32_e32 v32, 0
	v_mov_b32_e32 v33, 0
	v_mov_b32_e32 v34, 0
	v_mov_b32_e32 v35, 0
	v_mov_b32_e32 v36, 0
	v_mov_b32_e32 v37, 0
	v_mov_b32_e32 v38, 0
	v_mov_b32_e32 v39, 0
	v_mov_b32_e32 v40, 0
	v_mov_b32_e32 v41, 0
	v_mov_b32_e32 v42, 0
	v_mov_b32_e32 v43, 0
	v_mov_b32_e32 v44, 0
	v_mov_b32_e32 v45, 0
	v_mov_b32_e32 v46, 0
	v_mov_b32_e32 v47, 0
	v_mov_b32_e32 v16, 0
	v_mov_b32_e32 v17, 0
	v_mov_b32_e32 v18, 0
	v_mov_b32_e32 v19, 0
	v_mov_b32_e32 v20, 0
	v_mov_b32_e32 v21, 0
	v_mov_b32_e32 v22, 0
	v_mov_b32_e32 v23, 0
	v_mov_b32_e32 v24, 0
	v_mov_b32_e32 v25, 0
	v_mov_b32_e32 v26, 0
	v_mov_b32_e32 v27, 0
	v_mov_b32_e32 v28, 0
	v_mov_b32_e32 v29, 0
	v_mov_b32_e32 v30, 0
	v_mov_b32_e32 v31, 0
	v_mov_b32_e32 v0, 0
	v_mov_b32_e32 v1, 0
	v_mov_b32_e32 v2, 0
	v_mov_b32_e32 v3, 0
	v_mov_b32_e32 v4, 0
	v_mov_b32_e32 v5, 0
	v_mov_b32_e32 v6, 0
	v_mov_b32_e32 v7, 0
	v_mov_b32_e32 v8, 0
	v_mov_b32_e32 v9, 0
	v_mov_b32_e32 v10, 0
	v_mov_b32_e32 v11, 0
	v_mov_b32_e32 v12, 0
	v_mov_b32_e32 v13, 0
	v_mov_b32_e32 v14, 0
	v_mov_b32_e32 v15, 0
	v_add_u32_e32 v120, s16, v118
	v_add_u32_e32 v121, s16, v119
	s_mov_b32 s20, 0
	s_waitcnt vmcnt(23)
	s_barrier
	v_add_u32_e32 v122, v120, v211
	v_add_u32_e32 v123, v121, v211
	ds_read_b128 v[84:87], v122
	ds_read_b128 v[92:95], v123 offset:16384
	ds_read_b128 v[96:99], v123 offset:20480
	ds_read_b128 v[88:91], v122 offset:4096
.Lg2_loop:
	s_cmp_ge_u32 s20, 14
	s_cbranch_scc1 .Lg2_nodma
	s_add_i32 s21, s18, s19
	s_mov_b32 m0, s21
	s_nop 0
	global_load_lds_dwordx4 v124, s[12:13]
	s_add_i32 m0, s21, 0x2000
	s_nop 0
	global_load_lds_dwordx4 v125, s[12:13]
	s_add_i32 m0, s21, 0x4000
	s_nop 0
	global_load_lds_dwordx4 v124, s[14:15]
	s_add_i32 m0, s21, 0x6000
	s_nop 0
	global_load_lds_dwordx4 v125, s[14:15]
	s_add_i32 m0, s21, 0x8000
	s_nop 0
	global_load_lds_dwordx4 v126, s[14:15]
	s_add_i32 m0, s21, 0xa000
	s_nop 0
	global_load_lds_dwordx4 v127, s[14:15]
	s_add_u32 s12, s12, 0x80
	s_addc_u32 s13, s13, 0
	s_add_u32 s14, s14, 0x80
	s_addc_u32 s15, s15, 0
.Lg2_nodma:
	v_add_u32_e32 v122, v120, v212
	v_add_u32_e32 v123, v121, v212
	ds_read_b128 v[102:105], v122
	ds_read_b128 v[110:113], v123 offset:16384
	ds_read_b128 v[114:117], v123 offset:20480
	ds_read_b128 v[106:109], v122 offset:4096
	s_setprio 1
	s_waitcnt lgkmcnt(6)
	v_mfma_f32_32x32x16_bf16 v[48:63], v[84:87], v[92:95], v[48:63]
	s_waitcnt lgkmcnt(5)
	v_mfma_f32_32x32x16_bf16 v[32:47], v[84:87], v[96:99], v[32:47]
	s_waitcnt lgkmcnt(4)
	v_mfma_f32_32x32x16_bf16 v[16:31], v[88:91], v[92:95], v[16:31]
	v_mfma_f32_32x32x16_bf16 v[0:15], v[88:91], v[96:99], v[0:15]
	s_setprio 0
	v_add_u32_e32 v122, v120, v213
	v_add_u32_e32 v123, v121, v213
	ds_read_b128 v[84:87], v122
	ds_read_b128 v[92:95], v123 offset:16384
	ds_read_b128 v[96:99], v123 offset:20480
	ds_read_b128 v[88:91], v122 offset:4096
	s_setprio 1
	s_waitcnt lgkmcnt(6)
	v_mfma_f32_32x32x16_bf16 v[48:63], v[102:105], v[110:113], v[48:63]
	s_waitcnt lgkmcnt(5)
	v_mfma_f32_32x32x16_bf16 v[32:47], v[102:105], v[114:117], v[32:47]
	s_waitcnt lgkmcnt(4)
	v_mfma_f32_32x32x16_bf16 v[16:31], v[106:109], v[110:113], v[16:31]
	v_mfma_f32_32x32x16_bf16 v[0:15], v[106:109], v[114:117], v[0:15]
	s_setprio 0
	v_add_u32_e32 v122, v120, v214
	v_add_u32_e32 v123, v121, v214
	ds_read_b128 v[102:105], v122
	ds_read_b128 v[110:113], v123 offset:16384
	ds_read_b128 v[114:117], v123 offset:20480
	ds_read_b128 v[106:109], v122 offset:4096
	s_setprio 1
	s_waitcnt lgkmcnt(6)
	v_mfma_f32_32x32x16_bf16 v[48:63], v[84:87], v[92:95], v[48:63]
	s_waitcnt lgkmcnt(5)
	v_mfma_f32_32x32x16_bf16 v[32:47], v[84:87], v[96:99], v[32:47]
	s_waitcnt lgkmcnt(4)
	v_mfma_f32_32x32x16_bf16 v[16:31], v[88:91], v[92:95], v[16:31]
	v_mfma_f32_32x32x16_bf16 v[0:15], v[88:91], v[96:99], v[0:15]
	s_setprio 0
	s_waitcnt lgkmcnt(0)
	s_cmp_ge_u32 s20, 14
	s_cbranch_scc1 .Lg2_w0
	s_cmp_eq_u32 s20, 0
	s_cbranch_scc0 .Lg2_w6
	s_waitcnt vmcnt(23)
	s_branch .Lg2_wd
.Lg2_w6:
	s_waitcnt vmcnt(6)
	s_branch .Lg2_wd

.Lg2_wd:
	s_barrier
	s_add_i32 s20, s20, 1
	s_mov_b32 s21, s16
	s_mov_b32 s16, s17
	s_mov_b32 s17, s18
	s_mov_b32 s18, s21
	s_cmp_eq_u32 s20, 16
	s_cbranch_scc1 .Lg2_done
	v_add_u32_e32 v120, s16, v118
	v_add_u32_e32 v121, s16, v119
	v_add_u32_e32 v122, v120, v211
	v_add_u32_e32 v123, v121, v211
	ds_read_b128 v[84:87], v122
	ds_read_b128 v[92:95], v123 offset:16384
	ds_read_b128 v[96:99], v123 offset:20480
	ds_read_b128 v[88:91], v122 offset:4096
	s_setprio 1
	v_mfma_f32_32x32x16_bf16 v[48:63], v[102:105], v[110:113], v[48:63]
	v_mfma_f32_32x32x16_bf16 v[32:47], v[102:105], v[114:117], v[32:47]
	v_mfma_f32_32x32x16_bf16 v[16:31], v[106:109], v[110:113], v[16:31]
	v_mfma_f32_32x32x16_bf16 v[0:15], v[106:109], v[114:117], v[0:15]
	s_setprio 0
	s_branch .Lg2_loop
.Lg2_done:
	s_setprio 1
	v_mfma_f32_32x32x16_bf16 v[48:63], v[102:105], v[110:113], v[48:63]
	v_mfma_f32_32x32x16_bf16 v[32:47], v[102:105], v[114:117], v[32:47]
	v_mfma_f32_32x32x16_bf16 v[16:31], v[106:109], v[110:113], v[16:31]
	v_mfma_f32_32x32x16_bf16 v[0:15], v[106:109], v[114:117], v[0:15]
	s_setprio 0
	s_nop 7
	s_nop 3
	ds_write_b32 v240, v48
	ds_write_b32 v240, v49 offset:272
	ds_write_b32 v240, v50 offset:544
	ds_write_b32 v240, v51 offset:816
	ds_write_b32 v240, v52 offset:2176
	ds_write_b32 v240, v53 offset:2448
	ds_write_b32 v240, v54 offset:2720
	ds_write_b32 v240, v55 offset:2992
	ds_write_b32 v240, v56 offset:4352
	ds_write_b32 v240, v57 offset:4624
	ds_write_b32 v240, v58 offset:4896
	ds_write_b32 v240, v59 offset:5168
	ds_write_b32 v240, v60 offset:6528
	ds_write_b32 v240, v61 offset:6800
	ds_write_b32 v240, v62 offset:7072
	ds_write_b32 v240, v63 offset:7344
	ds_write_b32 v240, v32 offset:128
	ds_write_b32 v240, v33 offset:400
	ds_write_b32 v240, v34 offset:672
	ds_write_b32 v240, v35 offset:944
	ds_write_b32 v240, v36 offset:2304
	ds_write_b32 v240, v37 offset:2576
	ds_write_b32 v240, v38 offset:2848
	ds_write_b32 v240, v39 offset:3120
	ds_write_b32 v240, v40 offset:4480
	ds_write_b32 v240, v41 offset:4752
	ds_write_b32 v240, v42 offset:5024
	ds_write_b32 v240, v43 offset:5296
	ds_write_b32 v240, v44 offset:6656
	ds_write_b32 v240, v45 offset:6928
	ds_write_b32 v240, v46 offset:7200
	ds_write_b32 v240, v47 offset:7472
	ds_read_b128 v[224:227], v83
	ds_read_b128 v[228:231], v83 offset:1088
	ds_read_b128 v[232:235], v83 offset:2176
	ds_read_b128 v[236:239], v83 offset:3264
	s_waitcnt lgkmcnt(3)
	v_pk_fma_f32 v[130:131], v[66:67], v[226:227], v[130:131]
	v_pk_fma_f32 v[128:129], v[64:65], v[224:225], v[128:129]
	global_store_dwordx4 v216, v[128:131], s[24:25]
	s_waitcnt lgkmcnt(2)
	v_pk_fma_f32 v[134:135], v[66:67], v[230:231], v[134:135]
	v_pk_fma_f32 v[132:133], v[64:65], v[228:229], v[132:133]
	global_store_dwordx4 v217, v[132:135], s[24:25]
	s_waitcnt lgkmcnt(1)
	v_pk_fma_f32 v[138:139], v[66:67], v[234:235], v[138:139]
	v_pk_fma_f32 v[136:137], v[64:65], v[232:233], v[136:137]
	global_store_dwordx4 v218, v[136:139], s[24:25]
	s_waitcnt lgkmcnt(0)
	v_pk_fma_f32 v[142:143], v[66:67], v[238:239], v[142:143]
	v_pk_fma_f32 v[140:141], v[64:65], v[236:237], v[140:141]
	global_store_dwordx4 v219, v[140:143], s[24:25]
	ds_read_b128 v[224:227], v83 offset:4352
	ds_read_b128 v[228:231], v83 offset:5440
	ds_read_b128 v[232:235], v83 offset:6528
	ds_read_b128 v[236:239], v83 offset:7616
	s_waitcnt lgkmcnt(3)
	v_pk_fma_f32 v[146:147], v[66:67], v[226:227], v[146:147]
	v_pk_fma_f32 v[144:145], v[64:65], v[224:225], v[144:145]
	global_store_dwordx4 v220, v[144:147], s[24:25]
	s_waitcnt lgkmcnt(2)
	v_pk_fma_f32 v[150:151], v[66:67], v[230:231], v[150:151]
	v_pk_fma_f32 v[148:149], v[64:65], v[228:229], v[148:149]
	global_store_dwordx4 v221, v[148:151], s[24:25]
	s_waitcnt lgkmcnt(1)
	v_pk_fma_f32 v[154:155], v[66:67], v[234:235], v[154:155]
	v_pk_fma_f32 v[152:153], v[64:65], v[232:233], v[152:153]
	global_store_dwordx4 v222, v[152:155], s[24:25]
	s_waitcnt lgkmcnt(0)
	v_pk_fma_f32 v[158:159], v[66:67], v[238:239], v[158:159]
	v_pk_fma_f32 v[156:157], v[64:65], v[236:237], v[156:157]
	global_store_dwordx4 v223, v[156:159], s[24:25]
	ds_write_b32 v240, v16
	ds_write_b32 v240, v17 offset:272
	ds_write_b32 v240, v18 offset:544
	ds_write_b32 v240, v19 offset:816
	ds_write_b32 v240, v20 offset:2176
	ds_write_b32 v240, v21 offset:2448
	ds_write_b32 v240, v22 offset:2720
	ds_write_b32 v240, v23 offset:2992
	ds_write_b32 v240, v24 offset:4352
	ds_write_b32 v240, v25 offset:4624
	ds_write_b32 v240, v26 offset:4896
	ds_write_b32 v240, v27 offset:5168
	ds_write_b32 v240, v28 offset:6528
	ds_write_b32 v240, v29 offset:6800
	ds_write_b32 v240, v30 offset:7072
	ds_write_b32 v240, v31 offset:7344
	ds_write_b32 v240, v0 offset:128
	ds_write_b32 v240, v1 offset:400
	ds_write_b32 v240, v2 offset:672
	ds_write_b32 v240, v3 offset:944
	ds_write_b32 v240, v4 offset:2304
	ds_write_b32 v240, v5 offset:2576
	ds_write_b32 v240, v6 offset:2848
	ds_write_b32 v240, v7 offset:3120
	ds_write_b32 v240, v8 offset:4480
	ds_write_b32 v240, v9 offset:4752
	ds_write_b32 v240, v10 offset:5024
	ds_write_b32 v240, v11 offset:5296
	ds_write_b32 v240, v12 offset:6656
	ds_write_b32 v240, v13 offset:6928
	ds_write_b32 v240, v14 offset:7200
	ds_write_b32 v240, v15 offset:7472
	ds_read_b128 v[224:227], v83
	ds_read_b128 v[228:231], v83 offset:1088
	ds_read_b128 v[232:235], v83 offset:2176
	ds_read_b128 v[236:239], v83 offset:3264
	s_waitcnt lgkmcnt(3)
	v_pk_fma_f32 v[162:163], v[66:67], v[226:227], v[162:163]
	v_pk_fma_f32 v[160:161], v[64:65], v[224:225], v[160:161]
	global_store_dwordx4 v216, v[160:163], s[10:11]
	s_waitcnt lgkmcnt(2)
	v_pk_fma_f32 v[166:167], v[66:67], v[230:231], v[166:167]
	v_pk_fma_f32 v[164:165], v[64:65], v[228:229], v[164:165]
	global_store_dwordx4 v217, v[164:167], s[10:11]
	s_waitcnt lgkmcnt(1)
	v_pk_fma_f32 v[170:171], v[66:67], v[234:235], v[170:171]
	v_pk_fma_f32 v[168:169], v[64:65], v[232:233], v[168:169]
	global_store_dwordx4 v218, v[168:171], s[10:11]
	s_waitcnt lgkmcnt(0)
	v_pk_fma_f32 v[174:175], v[66:67], v[238:239], v[174:175]
	v_pk_fma_f32 v[172:173], v[64:65], v[236:237], v[172:173]
	global_store_dwordx4 v219, v[172:175], s[10:11]
	ds_read_b128 v[224:227], v83 offset:4352
	ds_read_b128 v[228:231], v83 offset:5440
	ds_read_b128 v[232:235], v83 offset:6528
	ds_read_b128 v[236:239], v83 offset:7616
	s_waitcnt lgkmcnt(3)
	v_pk_fma_f32 v[178:179], v[66:67], v[226:227], v[178:179]
	v_pk_fma_f32 v[176:177], v[64:65], v[224:225], v[176:177]
	global_store_dwordx4 v220, v[176:179], s[10:11]
	s_waitcnt lgkmcnt(2)
	v_pk_fma_f32 v[182:183], v[66:67], v[230:231], v[182:183]
	v_pk_fma_f32 v[180:181], v[64:65], v[228:229], v[180:181]
	global_store_dwordx4 v221, v[180:183], s[10:11]
	s_waitcnt lgkmcnt(1)
	v_pk_fma_f32 v[192:193], v[66:67], v[234:235], v[192:193]
	v_pk_fma_f32 v[190:191], v[64:65], v[232:233], v[190:191]
	global_store_dwordx4 v222, v[190:193], s[10:11]
	s_waitcnt lgkmcnt(0)
	v_pk_fma_f32 v[196:197], v[66:67], v[238:239], v[196:197]
	v_pk_fma_f32 v[194:195], v[64:65], v[236:237], v[194:195]
	global_store_dwordx4 v223, v[194:197], s[10:11]
	s_add_i32 s47, s47, s86
	s_cmp_ge_i32 s47, s3
	s_barrier
	s_cbranch_scc0 .LBB0_868

	.amdhsa_kernel _Z11mega_kernel6Params
		.amdhsa_group_segment_fixed_size 49408
		.amdhsa_private_segment_fixed_size 0
		.amdhsa_kernarg_size 464
		.amdhsa_user_sgpr_count 2
		.amdhsa_user_sgpr_dispatch_ptr 0
		.amdhsa_user_sgpr_queue_ptr 0
		.amdhsa_user_sgpr_kernarg_segment_ptr 1
		.amdhsa_user_sgpr_dispatch_id 0
		.amdhsa_user_sgpr_kernarg_preload_length 0
		.amdhsa_user_sgpr_kernarg_preload_offset 0
		.amdhsa_user_sgpr_private_segment_size 0
		.amdhsa_uses_dynamic_stack 0
		.amdhsa_enable_private_segment 0
		.amdhsa_system_sgpr_workgroup_id_x 1
		.amdhsa_system_sgpr_workgroup_id_y 1
		.amdhsa_system_sgpr_workgroup_id_z 1
		.amdhsa_system_sgpr_workgroup_info 0
		.amdhsa_system_vgpr_workitem_id 2
		.amdhsa_next_free_vgpr 248
		.amdhsa_next_free_sgpr 100
		.amdhsa_accum_offset 248
		.amdhsa_reserve_vcc 1
		.amdhsa_float_round_mode_32 0
		.amdhsa_float_round_mode_16_64 0
		.amdhsa_float_denorm_mode_32 3
		.amdhsa_float_denorm_mode_16_64 3
		.amdhsa_dx10_clamp 1
		.amdhsa_ieee_mode 1
		.amdhsa_fp16_overflow 0
		.amdhsa_tg_split 0
		.amdhsa_exception_fp_ieee_invalid_op 0
		.amdhsa_exception_fp_denorm_src 0
		.amdhsa_exception_fp_ieee_div_zero 0
		.amdhsa_exception_fp_ieee_overflow 0
		.amdhsa_exception_fp_ieee_underflow 0
		.amdhsa_exception_fp_ieee_inexact 0
		.amdhsa_exception_int_div_zero 0
	.end_amdhsa_kernel

amdhsa.kernels:
  - .agpr_count:     0
    .args:
      - .offset:         0
        .size:           208
        .value_kind:     by_value
      - .offset:         208
        .size:           4
        .value_kind:     hidden_block_count_x
      - .offset:         212
        .size:           4
        .value_kind:     hidden_block_count_y
      - .offset:         216
        .size:           4
        .value_kind:     hidden_block_count_z
      - .offset:         220
        .size:           2
        .value_kind:     hidden_group_size_x
      - .offset:         222
        .size:           2
        .value_kind:     hidden_group_size_y
      - .offset:         224
        .size:           2
        .value_kind:     hidden_group_size_z
      - .offset:         226
        .size:           2
        .value_kind:     hidden_remainder_x
      - .offset:         228
        .size:           2
        .value_kind:     hidden_remainder_y
      - .offset:         230
        .size:           2
        .value_kind:     hidden_remainder_z
      - .offset:         248
        .size:           8
        .value_kind:     hidden_global_offset_x
      - .offset:         256
        .size:           8
        .value_kind:     hidden_global_offset_y
      - .offset:         264
        .size:           8
        .value_kind:     hidden_global_offset_z
      - .offset:         272
        .size:           2
        .value_kind:     hidden_grid_dims
      - .offset:         328
        .size:           4
        .value_kind:     hidden_dynamic_lds_size
    .group_segment_fixed_size: 49408
    .kernarg_segment_align: 8
    .kernarg_segment_size: 464
    .language:       OpenCL C
    .language_version:
      - 2
      - 0
    .max_flat_workgroup_size: 512
    .name:           _Z11mega_kernel6Params
    .private_segment_fixed_size: 0
    .sgpr_count:     106
    .sgpr_spill_count: 85
    .symbol:         _Z11mega_kernel6Params.kd
    .uniform_work_group_size: 1
    .uses_dynamic_stack: false
    .vgpr_count:     248
    .vgpr_spill_count: 0
    .wavefront_size: 64
